# attention loops: PV V-fragment reads for d-groups 0,1 prefetched into dead K-fragment registers right after the QK MFMAs; groups 2,3 double-buffered (MFMA/LDS interleave); on top of v019
# speedup vs baseline: 1.0019x; 1.0019x over previous
; __device__ __forceinline__ void qkt(f32x16& p0, f32x16& p1, const LAS unsigned char* Kt, int r32, int hi, const bf16x8* qr, float init) {
;     f32x16 zi;
; #pragma unroll
;     for (int r = 0; r < 16; ++r) zi[r] = init;
;     const int kt = (int)(uintptr_t)Kt;
;     const int a0 = kt + KSWZ(r32, (0 * 16 + hi * 8) * 2), a1 = kt + KSWZ(r32, (1 * 16 + hi * 8) * 2), a2 = kt + KSWZ(r32, (2 * 16 + hi * 8) * 2), a3 = kt + KSWZ(r32, (3 * 16 + hi * 8) * 2);
;     ...
;     bf16x8 f0, f1, f2, f3, g0, g1, g2, g3, f4, f5, f6, f7, g4, g5, g6, g7;
;     DSR128(f0, a0, 0); DSR128(g0, a0, 8192); DSR128(f1, a1, 0); DSR128(g1, a1, 8192); DSR128(f2, a2, 0); DSR128(g2, a2, 8192); DSR128(f3, a3, 0); DSR128(g3, a3, 8192);
;     asm volatile("s_waitcnt lgkmcnt(0)" : "+v"(f0), "+v"(g0), "+v"(f1), "+v"(g1), "+v"(f2), "+v"(g2), "+v"(f3), "+v"(g3) :: "memory");
;     DSR128(f4, a0, 128); DSR128(g4, a0, 8320); DSR128(f5, a1, 128); DSR128(g5, a1, 8320); DSR128(f6, a2, 128); DSR128(g6, a2, 8320); DSR128(f7, a3, 128); DSR128(g7, a3, 8320);
;     SBAR();
;     p0 = __builtin_amdgcn_mfma_f32_32x32x16_bf16(f0, qr[0], zi, 0, 0, 0); p1 = __builtin_amdgcn_mfma_f32_32x32x16_bf16(g0, qr[0], zi, 0, 0, 0);
;     p0 = __builtin_amdgcn_mfma_f32_32x32x16_bf16(f1, qr[1], p0, 0, 0, 0); p1 = __builtin_amdgcn_mfma_f32_32x32x16_bf16(g1, qr[1], p1, 0, 0, 0);
;     p0 = __builtin_amdgcn_mfma_f32_32x32x16_bf16(f2, qr[2], p0, 0, 0, 0); p1 = __builtin_amdgcn_mfma_f32_32x32x16_bf16(g2, qr[2], p1, 0, 0, 0);
;     p0 = __builtin_amdgcn_mfma_f32_32x32x16_bf16(f3, qr[3], p0, 0, 0, 0); p1 = __builtin_amdgcn_mfma_f32_32x32x16_bf16(g3, qr[3], p1, 0, 0, 0);
;     asm volatile("s_waitcnt lgkmcnt(0)" : "+v"(f4), "+v"(g4), "+v"(f5), "+v"(g5), "+v"(f6), "+v"(g6), "+v"(f7), "+v"(g7) :: "memory");
;     SBAR();
;     p0 = __builtin_amdgcn_mfma_f32_32x32x16_bf16(f4, qr[4], p0, 0, 0, 0); p1 = __builtin_amdgcn_mfma_f32_32x32x16_bf16(g4, qr[4], p1, 0, 0, 0);
;     p0 = __builtin_amdgcn_mfma_f32_32x32x16_bf16(f5, qr[5], p0, 0, 0, 0); p1 = __builtin_amdgcn_mfma_f32_32x32x16_bf16(g5, qr[5], p1, 0, 0, 0);
;     p0 = __builtin_amdgcn_mfma_f32_32x32x16_bf16(f6, qr[6], p0, 0, 0, 0); p1 = __builtin_amdgcn_mfma_f32_32x32x16_bf16(g6, qr[6], p1, 0, 0, 0);
;     p0 = __builtin_amdgcn_mfma_f32_32x32x16_bf16(f7, qr[7], p0, 0, 0, 0); p1 = __builtin_amdgcn_mfma_f32_32x32x16_bf16(g7, qr[7], p1, 0, 0, 0);
;     ...
; }
.Lmy_ldskip_0:
	s_add_i32 s11, s0, 0
	s_add_i32 s0, s11, 0xc000
	v_bfe_u32 v2, v160, s12, 1
	v_cmp_eq_u32_e32 vcc, 0, v2
	v_add_u32_e32 v2, s0, v172
	ds_read_b128 v[182:185], v2 offset:0
	ds_read_b128 v[186:189], v2 offset:0x2000
	v_add_u32_e32 v84, s0, v173
	ds_read_b128 v[190:193], v84 offset:0
	ds_read_b128 v[194:197], v84 offset:0x2000
	v_add_u32_e32 v85, s0, v174
	ds_read_b128 v[198:201], v85 offset:0
	ds_read_b128 v[202:205], v85 offset:0x2000
	v_add_u32_e32 v86, s0, v175
	ds_read_b128 v[206:209], v86 offset:0
	ds_read_b128 v[210:213], v86 offset:0x2000
	v_cndmask_b32_e32 v68, 0, v163, vcc
	s_waitcnt lgkmcnt(0)
	ds_read_b128 v[214:217], v2 offset:0x80
	ds_read_b128 v[218:221], v2 offset:0x2080
	ds_read_b128 v[222:225], v84 offset:0x80
	ds_read_b128 v[226:229], v84 offset:0x2080
	ds_read_b128 v[230:233], v85 offset:0x80
	ds_read_b128 v[234:237], v85 offset:0x2080
	ds_read_b128 v[238:241], v86 offset:0x80
	ds_read_b128 v[242:245], v86 offset:0x2080
	v_mov_b32_e32 v69, v68
	v_mov_b32_e32 v70, v68
	v_mov_b32_e32 v71, v68
	v_mov_b32_e32 v72, v68
	v_mov_b32_e32 v73, v68
	v_mov_b32_e32 v74, v68
	v_mov_b32_e32 v75, v68
	v_mov_b32_e32 v76, v68
	v_mov_b32_e32 v77, v68
	v_mov_b32_e32 v78, v68
	v_mov_b32_e32 v79, v68
	v_mov_b32_e32 v80, v68
	v_mov_b32_e32 v81, v68
	v_mov_b32_e32 v82, v68
	v_mov_b32_e32 v83, v68
	s_nop 1
	v_mfma_f32_32x32x16_bf16 v[84:99], v[182:185], v[100:103], v[68:83]
	v_mfma_f32_32x32x16_bf16 v[68:83], v[186:189], v[100:103], v[68:83]
	v_mfma_f32_32x32x16_bf16 v[84:99], v[190:193], v[104:107], v[84:99]
	v_mfma_f32_32x32x16_bf16 v[68:83], v[194:197], v[104:107], v[68:83]
	v_mfma_f32_32x32x16_bf16 v[84:99], v[198:201], v[108:111], v[84:99]
	v_mfma_f32_32x32x16_bf16 v[68:83], v[202:205], v[108:111], v[68:83]
	v_mfma_f32_32x32x16_bf16 v[84:99], v[206:209], v[112:115], v[84:99]
	v_mfma_f32_32x32x16_bf16 v[68:83], v[210:213], v[112:115], v[68:83]
	s_waitcnt lgkmcnt(0)
	v_mfma_f32_32x32x16_bf16 v[84:99], v[214:217], v[116:119], v[84:99]
	s_cmp_ge_i32 s76, s95
	v_mfma_f32_32x32x16_bf16 v[68:83], v[218:221], v[116:119], v[68:83]
	v_mfma_f32_32x32x16_bf16 v[84:99], v[222:225], v[120:123], v[84:99]
	v_mfma_f32_32x32x16_bf16 v[68:83], v[226:229], v[120:123], v[68:83]
	v_mfma_f32_32x32x16_bf16 v[84:99], v[230:233], v[124:127], v[84:99]
	v_mfma_f32_32x32x16_bf16 v[68:83], v[234:237], v[124:127], v[68:83]
	v_mfma_f32_32x32x16_bf16 v[84:99], v[238:241], v[128:131], v[84:99]
	v_mfma_f32_32x32x16_bf16 v[68:83], v[242:245], v[128:131], v[68:83]
	s_mul_i32 s99, s10, 0x4000
	v_add_u32_e32 v247, s99, v178
	ds_read_b64_tr_b16 v[214:215], v247 offset:0
	ds_read_b64_tr_b16 v[216:217], v247 offset:2048
	ds_read_b64_tr_b16 v[218:219], v247 offset:4096
	ds_read_b64_tr_b16 v[220:221], v247 offset:6144
	ds_read_b64_tr_b16 v[222:223], v247 offset:8192
	ds_read_b64_tr_b16 v[224:225], v247 offset:10240
	ds_read_b64_tr_b16 v[226:227], v247 offset:12288
	ds_read_b64_tr_b16 v[228:229], v247 offset:14336
	ds_read_b64_tr_b16 v[230:231], v247 offset:512
	ds_read_b64_tr_b16 v[232:233], v247 offset:2560
	ds_read_b64_tr_b16 v[234:235], v247 offset:4608
	ds_read_b64_tr_b16 v[236:237], v247 offset:6656
	ds_read_b64_tr_b16 v[238:239], v247 offset:8704
	ds_read_b64_tr_b16 v[240:241], v247 offset:10752
	ds_read_b64_tr_b16 v[242:243], v247 offset:12800
	ds_read_b64_tr_b16 v[244:245], v247 offset:14848
	s_cbranch_scc1 .LBB0_3060
	ds_read_b32 v182, v179 offset:0xec
	ds_read_b32 v184, v179 offset:0x6c
	ds_read_b32 v183, v179 offset:0xe8
	ds_read_b32 v185, v179 offset:0x68
	ds_read_b32 v186, v179 offset:0xe4
	ds_read_b32 v188, v179 offset:0x64
	ds_read_b32 v187, v179 offset:0xe0
	ds_read_b32 v189, v179 offset:0x60
	ds_read_b32 v190, v179 offset:0xcc
	ds_read_b32 v192, v179 offset:0x4c
	ds_read_b32 v191, v179 offset:0xc8
	ds_read_b32 v193, v179 offset:0x48
	ds_read_b32 v194, v179 offset:0xc4
	ds_read_b32 v196, v179 offset:0x44
	ds_read_b32 v195, v179 offset:0xc0
	ds_read_b32 v197, v179 offset:64
	ds_read_b32 v198, v179 offset:0xac
	ds_read_b32 v200, v179 offset:44
	ds_read_b32 v199, v179 offset:0xa8
	ds_read_b32 v201, v179 offset:40
	ds_read_b32 v202, v179 offset:0xa4
	ds_read_b32 v204, v179 offset:36
	ds_read_b32 v203, v179 offset:0xa0
	ds_read_b32 v205, v179 offset:32
	ds_read_b32 v206, v179 offset:0x8c
	ds_read_b32 v208, v179 offset:12
	ds_read_b32 v207, v179 offset:0x88
	ds_read_b32 v209, v179 offset:8
	ds_read_b32 v210, v179 offset:0x84
	ds_read_b32 v212, v179 offset:4
	ds_read_b32 v211, v179 offset:0x80
	ds_read_b32 v213, v179 offset:0
	s_nop 0
	s_waitcnt lgkmcnt(0)
	s_nop 8
	v_pk_add_f32 v[98:99], v[98:99], v[210:211]
	v_pk_add_f32 v[96:97], v[96:97], v[206:207]
	v_pk_add_f32 v[94:95], v[94:95], v[202:203]
	v_pk_add_f32 v[92:93], v[92:93], v[198:199]
	v_pk_add_f32 v[90:91], v[90:91], v[194:195]
	v_pk_add_f32 v[88:89], v[88:89], v[190:191]
	v_pk_add_f32 v[86:87], v[86:87], v[186:187]
	v_pk_add_f32 v[84:85], v[84:85], v[182:183]
	v_pk_add_f32 v[82:83], v[82:83], v[212:213]
	v_pk_add_f32 v[80:81], v[80:81], v[208:209]
	v_pk_add_f32 v[78:79], v[78:79], v[204:205]
	v_pk_add_f32 v[76:77], v[76:77], v[200:201]
	v_pk_add_f32 v[74:75], v[74:75], v[196:197]
	v_pk_add_f32 v[72:73], v[72:73], v[192:193]
	v_pk_add_f32 v[70:71], v[70:71], v[188:189]
	v_pk_add_f32 v[68:69], v[68:69], v[184:185]

; __device__ __forceinline__ void pv_tile(f32x16* o, int vb, bf16x8 pa0, bf16x8 pa1, bf16x8 pa2, bf16x8 pa3) {
;     ...
;     PV_D0(0); PV_D0(1); PV_D0(2); PV_D0(3);
;     ...
; }
; template <int MODE>
; __device__ __forceinline__ void attn_branch(Frame& F, const bf16_t* Kp, const bf16_t* Vp, int j_lo, int j_hi, int sb, const bf16x8* qr, unsigned smask, f32x16* o, float& l_out) {
;     ...
;         if (t + 2 < NT) tile_write(T, lds, t & 1, vs == 0 ? 2 : vs - 1, sr, sc);
.LBB0_3069:
	s_lshl_b32 s12, s10, 14
	s_waitcnt lgkmcnt(0)
	s_nop 0
	v_mfma_f32_32x32x16_bf16 v[52:67], v[68:71], v[214:217], v[52:67]
	ds_read_b64_tr_b16 v[214:215], v247 offset:1024
	ds_read_b64_tr_b16 v[216:217], v247 offset:3072
	v_mfma_f32_32x32x16_bf16 v[52:67], v[72:75], v[218:221], v[52:67]
	ds_read_b64_tr_b16 v[218:219], v247 offset:5120
	ds_read_b64_tr_b16 v[220:221], v247 offset:7168
	v_mfma_f32_32x32x16_bf16 v[52:67], v[80:83], v[222:225], v[52:67]
	ds_read_b64_tr_b16 v[222:223], v247 offset:9216
	ds_read_b64_tr_b16 v[224:225], v247 offset:11264
	v_mfma_f32_32x32x16_bf16 v[52:67], v[76:79], v[226:229], v[52:67]
	ds_read_b64_tr_b16 v[226:227], v247 offset:13312
	ds_read_b64_tr_b16 v[228:229], v247 offset:15360
	v_mfma_f32_32x32x16_bf16 v[36:51], v[68:71], v[230:233], v[36:51]
	ds_read_b64_tr_b16 v[230:231], v247 offset:1536
	ds_read_b64_tr_b16 v[232:233], v247 offset:3584
	v_mfma_f32_32x32x16_bf16 v[36:51], v[72:75], v[234:237], v[36:51]
	ds_read_b64_tr_b16 v[234:235], v247 offset:5632
	ds_read_b64_tr_b16 v[236:237], v247 offset:7680
	v_mfma_f32_32x32x16_bf16 v[36:51], v[80:83], v[238:241], v[36:51]
	ds_read_b64_tr_b16 v[238:239], v247 offset:9728
	ds_read_b64_tr_b16 v[240:241], v247 offset:11776
	v_mfma_f32_32x32x16_bf16 v[36:51], v[76:79], v[242:245], v[36:51]
	ds_read_b64_tr_b16 v[242:243], v247 offset:13824
	ds_read_b64_tr_b16 v[244:245], v247 offset:15872
	s_waitcnt lgkmcnt(8)
	s_nop 0
	v_mfma_f32_32x32x16_bf16 v[20:35], v[68:71], v[214:217], v[20:35]
	v_mfma_f32_32x32x16_bf16 v[20:35], v[72:75], v[218:221], v[20:35]
	v_mfma_f32_32x32x16_bf16 v[20:35], v[80:83], v[222:225], v[20:35]
	v_mfma_f32_32x32x16_bf16 v[20:35], v[76:79], v[226:229], v[20:35]
	s_waitcnt lgkmcnt(0)
	s_nop 0
	v_mfma_f32_32x32x16_bf16 v[4:19], v[68:71], v[230:233], v[4:19]
	v_mfma_f32_32x32x16_bf16 v[4:19], v[72:75], v[234:237], v[4:19]
	v_mfma_f32_32x32x16_bf16 v[4:19], v[80:83], v[238:241], v[4:19]
	v_mfma_f32_32x32x16_bf16 v[4:19], v[76:79], v[242:245], v[4:19]
	s_andn2_b64 vcc, exec, s[0:1]
	s_cbranch_vccnz .LBB0_3071
	s_addk_i32 s12, 0xc000
	s_cmp_lg_u32 s10, 0
	s_cselect_b32 s0, s12, 0x8000
	v_add_u32_e32 v68, s0, v169
	v_add3_u32 v70, s11, v161, v167
	v_add3_u32 v69, v68, v171, v168
	v_add3_u32 v68, v68, v170, v168
	s_waitcnt vmcnt(3)
	ds_write_b128 v70, v[132:135] offset:49152
	s_waitcnt vmcnt(2)
	ds_write_b128 v70, v[136:139] offset:57344
	s_waitcnt vmcnt(1)
	ds_write_b128 v68, v[140:143]
	s_waitcnt vmcnt(0)
	ds_write_b128 v69, v[144:147]

; __device__ __forceinline__ void qkt(f32x16& p0, f32x16& p1, const LAS unsigned char* Kt, int r32, int hi, const bf16x8* qr, float init) {
;     f32x16 zi;
; #pragma unroll
;     for (int r = 0; r < 16; ++r) zi[r] = init;
;     const int kt = (int)(uintptr_t)Kt;
;     const int a0 = kt + KSWZ(r32, (0 * 16 + hi * 8) * 2), a1 = kt + KSWZ(r32, (1 * 16 + hi * 8) * 2), a2 = kt + KSWZ(r32, (2 * 16 + hi * 8) * 2), a3 = kt + KSWZ(r32, (3 * 16 + hi * 8) * 2);
;     ...
;     bf16x8 f0, f1, f2, f3, g0, g1, g2, g3, f4, f5, f6, f7, g4, g5, g6, g7;
;     DSR128(f0, a0, 0); DSR128(g0, a0, 8192); DSR128(f1, a1, 0); DSR128(g1, a1, 8192); DSR128(f2, a2, 0); DSR128(g2, a2, 8192); DSR128(f3, a3, 0); DSR128(g3, a3, 8192);
;     asm volatile("s_waitcnt lgkmcnt(0)" : "+v"(f0), "+v"(g0), "+v"(f1), "+v"(g1), "+v"(f2), "+v"(g2), "+v"(f3), "+v"(g3) :: "memory");
;     DSR128(f4, a0, 128); DSR128(g4, a0, 8320); DSR128(f5, a1, 128); DSR128(g5, a1, 8320); DSR128(f6, a2, 128); DSR128(g6, a2, 8320); DSR128(f7, a3, 128); DSR128(g7, a3, 8320);
;     SBAR();
;     p0 = __builtin_amdgcn_mfma_f32_32x32x16_bf16(f0, qr[0], zi, 0, 0, 0); p1 = __builtin_amdgcn_mfma_f32_32x32x16_bf16(g0, qr[0], zi, 0, 0, 0);
;     p0 = __builtin_amdgcn_mfma_f32_32x32x16_bf16(f1, qr[1], p0, 0, 0, 0); p1 = __builtin_amdgcn_mfma_f32_32x32x16_bf16(g1, qr[1], p1, 0, 0, 0);
;     p0 = __builtin_amdgcn_mfma_f32_32x32x16_bf16(f2, qr[2], p0, 0, 0, 0); p1 = __builtin_amdgcn_mfma_f32_32x32x16_bf16(g2, qr[2], p1, 0, 0, 0);
;     p0 = __builtin_amdgcn_mfma_f32_32x32x16_bf16(f3, qr[3], p0, 0, 0, 0); p1 = __builtin_amdgcn_mfma_f32_32x32x16_bf16(g3, qr[3], p1, 0, 0, 0);
;     asm volatile("s_waitcnt lgkmcnt(0)" : "+v"(f4), "+v"(g4), "+v"(f5), "+v"(g5), "+v"(f6), "+v"(g6), "+v"(f7), "+v"(g7) :: "memory");
;     SBAR();
;     p0 = __builtin_amdgcn_mfma_f32_32x32x16_bf16(f4, qr[4], p0, 0, 0, 0); p1 = __builtin_amdgcn_mfma_f32_32x32x16_bf16(g4, qr[4], p1, 0, 0, 0);
;     p0 = __builtin_amdgcn_mfma_f32_32x32x16_bf16(f5, qr[5], p0, 0, 0, 0); p1 = __builtin_amdgcn_mfma_f32_32x32x16_bf16(g5, qr[5], p1, 0, 0, 0);
;     p0 = __builtin_amdgcn_mfma_f32_32x32x16_bf16(f6, qr[6], p0, 0, 0, 0); p1 = __builtin_amdgcn_mfma_f32_32x32x16_bf16(g6, qr[6], p1, 0, 0, 0);
;     p0 = __builtin_amdgcn_mfma_f32_32x32x16_bf16(f7, qr[7], p0, 0, 0, 0); p1 = __builtin_amdgcn_mfma_f32_32x32x16_bf16(g7, qr[7], p1, 0, 0, 0);
;     ...
; }
.Lmy_ldskip_1:
	s_add_i32 s15, s0, 0
	s_add_i32 s0, s15, 0xc000
	v_add_u32_e32 v2, s0, v171
	ds_read_b128 v[68:71], v2 offset:0
	ds_read_b128 v[72:75], v2 offset:0x2000
	v_add_u32_e32 v76, s0, v172
	ds_read_b128 v[182:185], v76 offset:0
	ds_read_b128 v[186:189], v76 offset:0x2000
	v_add_u32_e32 v77, s0, v173
	ds_read_b128 v[190:193], v77 offset:0
	ds_read_b128 v[194:197], v77 offset:0x2000
	v_add_u32_e32 v78, s0, v174
	ds_read_b128 v[198:201], v78 offset:0
	ds_read_b128 v[202:205], v78 offset:0x2000
	s_nop 0
	s_waitcnt lgkmcnt(0)
	ds_read_b128 v[206:209], v2 offset:0x80
	ds_read_b128 v[210:213], v2 offset:0x2080
	ds_read_b128 v[214:217], v76 offset:0x80
	ds_read_b128 v[218:221], v76 offset:0x2080
	ds_read_b128 v[222:225], v77 offset:0x80
	ds_read_b128 v[226:229], v77 offset:0x2080
	ds_read_b128 v[230:233], v78 offset:0x80
	ds_read_b128 v[234:237], v78 offset:0x2080
	s_nop 0
	v_mfma_f32_32x32x16_bf16 v[84:99], v[68:71], v[100:103], 0
	v_mfma_f32_32x32x16_bf16 v[68:83], v[72:75], v[100:103], 0
	v_mfma_f32_32x32x16_bf16 v[84:99], v[182:185], v[104:107], v[84:99]
	v_mfma_f32_32x32x16_bf16 v[68:83], v[186:189], v[104:107], v[68:83]
	v_mfma_f32_32x32x16_bf16 v[84:99], v[190:193], v[108:111], v[84:99]
	v_mfma_f32_32x32x16_bf16 v[68:83], v[194:197], v[108:111], v[68:83]
	v_mfma_f32_32x32x16_bf16 v[84:99], v[198:201], v[112:115], v[84:99]
	v_mfma_f32_32x32x16_bf16 v[68:83], v[202:205], v[112:115], v[68:83]
	s_waitcnt lgkmcnt(0)
	v_mfma_f32_32x32x16_bf16 v[84:99], v[206:209], v[116:119], v[84:99]
	s_add_i32 s0, s12, s13
	s_cmp_ge_i32 s0, s95
	v_mfma_f32_32x32x16_bf16 v[68:83], v[210:213], v[116:119], v[68:83]
	v_mfma_f32_32x32x16_bf16 v[84:99], v[214:217], v[120:123], v[84:99]
	v_mfma_f32_32x32x16_bf16 v[68:83], v[218:221], v[120:123], v[68:83]
	v_mfma_f32_32x32x16_bf16 v[84:99], v[222:225], v[124:127], v[84:99]
	v_mfma_f32_32x32x16_bf16 v[68:83], v[226:229], v[124:127], v[68:83]
	v_mfma_f32_32x32x16_bf16 v[84:99], v[230:233], v[128:131], v[84:99]
	v_mfma_f32_32x32x16_bf16 v[68:83], v[234:237], v[128:131], v[68:83]
	s_mul_i32 s99, s14, 0x4000
	v_add_u32_e32 v247, s99, v177
	ds_read_b64_tr_b16 v[214:215], v247 offset:0
	ds_read_b64_tr_b16 v[216:217], v247 offset:2048
	ds_read_b64_tr_b16 v[218:219], v247 offset:4096
	ds_read_b64_tr_b16 v[220:221], v247 offset:6144
	ds_read_b64_tr_b16 v[222:223], v247 offset:8192
	ds_read_b64_tr_b16 v[224:225], v247 offset:10240
	ds_read_b64_tr_b16 v[226:227], v247 offset:12288
	ds_read_b64_tr_b16 v[228:229], v247 offset:14336
	ds_read_b64_tr_b16 v[230:231], v247 offset:512
	ds_read_b64_tr_b16 v[232:233], v247 offset:2560
	ds_read_b64_tr_b16 v[234:235], v247 offset:4608
	ds_read_b64_tr_b16 v[236:237], v247 offset:6656
	ds_read_b64_tr_b16 v[238:239], v247 offset:8704
	ds_read_b64_tr_b16 v[240:241], v247 offset:10752
	ds_read_b64_tr_b16 v[242:243], v247 offset:12800
	ds_read_b64_tr_b16 v[244:245], v247 offset:14848
	s_cbranch_scc1 .LBB0_3083
	ds_read_b32 v182, v178 offset:0xec
	ds_read_b32 v184, v178 offset:0x6c
	ds_read_b32 v183, v178 offset:0xe8
	ds_read_b32 v185, v178 offset:0x68
	ds_read_b32 v186, v178 offset:0xe4
	ds_read_b32 v188, v178 offset:0x64
	ds_read_b32 v187, v178 offset:0xe0
	ds_read_b32 v189, v178 offset:0x60
	ds_read_b32 v190, v178 offset:0xcc
	ds_read_b32 v192, v178 offset:0x4c
	ds_read_b32 v191, v178 offset:0xc8
	ds_read_b32 v193, v178 offset:0x48
	ds_read_b32 v194, v178 offset:0xc4
	ds_read_b32 v196, v178 offset:0x44
	ds_read_b32 v195, v178 offset:0xc0
	ds_read_b32 v197, v178 offset:64
	ds_read_b32 v198, v178 offset:0xac
	ds_read_b32 v200, v178 offset:44
	ds_read_b32 v199, v178 offset:0xa8
	ds_read_b32 v201, v178 offset:40
	ds_read_b32 v202, v178 offset:0xa4
	ds_read_b32 v204, v178 offset:36
	ds_read_b32 v203, v178 offset:0xa0
	ds_read_b32 v205, v178 offset:32
	ds_read_b32 v206, v178 offset:0x8c
	ds_read_b32 v208, v178 offset:12
	ds_read_b32 v207, v178 offset:0x88
	ds_read_b32 v209, v178 offset:8
	ds_read_b32 v210, v178 offset:0x84
	ds_read_b32 v212, v178 offset:4
	ds_read_b32 v211, v178 offset:0x80
	ds_read_b32 v213, v178 offset:0
	s_nop 0
	s_waitcnt lgkmcnt(0)
	s_nop 8
	v_pk_add_f32 v[98:99], v[98:99], v[210:211]
	v_pk_add_f32 v[96:97], v[96:97], v[206:207]
	v_pk_add_f32 v[94:95], v[94:95], v[202:203]
	v_pk_add_f32 v[92:93], v[92:93], v[198:199]
	v_pk_add_f32 v[90:91], v[90:91], v[194:195]
	v_pk_add_f32 v[88:89], v[88:89], v[190:191]
	v_pk_add_f32 v[86:87], v[86:87], v[186:187]
	v_pk_add_f32 v[84:85], v[84:85], v[182:183]
	v_pk_add_f32 v[82:83], v[82:83], v[212:213]
	v_pk_add_f32 v[80:81], v[80:81], v[208:209]
	v_pk_add_f32 v[78:79], v[78:79], v[204:205]
	v_pk_add_f32 v[76:77], v[76:77], v[200:201]
	v_pk_add_f32 v[74:75], v[74:75], v[196:197]
	v_pk_add_f32 v[72:73], v[72:73], v[192:193]
	v_pk_add_f32 v[70:71], v[70:71], v[188:189]
	v_pk_add_f32 v[68:69], v[68:69], v[184:185]

; __device__ __forceinline__ void pv_tile(f32x16* o, int vb, bf16x8 pa0, bf16x8 pa1, bf16x8 pa2, bf16x8 pa3) {
;     ...
;     PV_D0(0); PV_D0(1); PV_D0(2); PV_D0(3);
;     ...
; }
; template <int MODE>
; __device__ __forceinline__ void attn_branch(Frame& F, const bf16_t* Kp, const bf16_t* Vp, int j_lo, int j_hi, int sb, const bf16x8* qr, unsigned smask, f32x16* o, float& l_out) {
;     ...
;         if (t + 2 < NT) tile_write(T, lds, t & 1, vs == 0 ? 2 : vs - 1, sr, sc);
.LBB0_3092:
	s_lshl_b32 s16, s14, 14
	s_waitcnt lgkmcnt(0)
	s_nop 0
	v_mfma_f32_32x32x16_bf16 v[52:67], v[68:71], v[214:217], v[52:67]
	ds_read_b64_tr_b16 v[214:215], v247 offset:1024
	ds_read_b64_tr_b16 v[216:217], v247 offset:3072
	v_mfma_f32_32x32x16_bf16 v[52:67], v[72:75], v[218:221], v[52:67]
	ds_read_b64_tr_b16 v[218:219], v247 offset:5120
	ds_read_b64_tr_b16 v[220:221], v247 offset:7168
	v_mfma_f32_32x32x16_bf16 v[52:67], v[80:83], v[222:225], v[52:67]
	ds_read_b64_tr_b16 v[222:223], v247 offset:9216
	ds_read_b64_tr_b16 v[224:225], v247 offset:11264
	v_mfma_f32_32x32x16_bf16 v[52:67], v[76:79], v[226:229], v[52:67]
	ds_read_b64_tr_b16 v[226:227], v247 offset:13312
	ds_read_b64_tr_b16 v[228:229], v247 offset:15360
	v_mfma_f32_32x32x16_bf16 v[36:51], v[68:71], v[230:233], v[36:51]
	ds_read_b64_tr_b16 v[230:231], v247 offset:1536
	ds_read_b64_tr_b16 v[232:233], v247 offset:3584
	v_mfma_f32_32x32x16_bf16 v[36:51], v[72:75], v[234:237], v[36:51]
	ds_read_b64_tr_b16 v[234:235], v247 offset:5632
	ds_read_b64_tr_b16 v[236:237], v247 offset:7680
	v_mfma_f32_32x32x16_bf16 v[36:51], v[80:83], v[238:241], v[36:51]
	ds_read_b64_tr_b16 v[238:239], v247 offset:9728
	ds_read_b64_tr_b16 v[240:241], v247 offset:11776
	v_mfma_f32_32x32x16_bf16 v[36:51], v[76:79], v[242:245], v[36:51]
	ds_read_b64_tr_b16 v[242:243], v247 offset:13824
	ds_read_b64_tr_b16 v[244:245], v247 offset:15872
	s_waitcnt lgkmcnt(8)
	s_nop 0
	v_mfma_f32_32x32x16_bf16 v[20:35], v[68:71], v[214:217], v[20:35]
	v_mfma_f32_32x32x16_bf16 v[20:35], v[72:75], v[218:221], v[20:35]
	v_mfma_f32_32x32x16_bf16 v[20:35], v[80:83], v[222:225], v[20:35]
	v_mfma_f32_32x32x16_bf16 v[20:35], v[76:79], v[226:229], v[20:35]
	s_waitcnt lgkmcnt(0)
	s_nop 0
	v_mfma_f32_32x32x16_bf16 v[4:19], v[68:71], v[230:233], v[4:19]
	v_mfma_f32_32x32x16_bf16 v[4:19], v[72:75], v[234:237], v[4:19]
	v_mfma_f32_32x32x16_bf16 v[4:19], v[80:83], v[238:241], v[4:19]
	v_mfma_f32_32x32x16_bf16 v[4:19], v[76:79], v[242:245], v[4:19]
	s_andn2_b64 vcc, exec, s[0:1]
	s_cbranch_vccnz .LBB0_3094
	s_addk_i32 s16, 0xc000
	s_cmp_lg_u32 s14, 0
	s_cselect_b32 s0, s16, 0x8000
	v_add_u32_e32 v68, s0, v169
	v_add3_u32 v70, s15, v160, v161
	v_add3_u32 v69, v68, v170, v168
	v_add3_u32 v68, v68, v167, v168
	s_waitcnt vmcnt(3)
	ds_write_b128 v70, v[132:135] offset:49152
	s_waitcnt vmcnt(2)
	ds_write_b128 v70, v[136:139] offset:57344
	s_waitcnt vmcnt(1)
	ds_write_b128 v68, v[140:143]
	s_waitcnt vmcnt(0)
	ds_write_b128 v69, v[144:147]

; __device__ __forceinline__ void qkt(f32x16& p0, f32x16& p1, const LAS unsigned char* Kt, int r32, int hi, const bf16x8* qr, float init) {
;     f32x16 zi;
; #pragma unroll
;     for (int r = 0; r < 16; ++r) zi[r] = init;
;     const int kt = (int)(uintptr_t)Kt;
;     const int a0 = kt + KSWZ(r32, (0 * 16 + hi * 8) * 2), a1 = kt + KSWZ(r32, (1 * 16 + hi * 8) * 2), a2 = kt + KSWZ(r32, (2 * 16 + hi * 8) * 2), a3 = kt + KSWZ(r32, (3 * 16 + hi * 8) * 2);
;     ...
;     bf16x8 f0, f1, f2, f3, g0, g1, g2, g3, f4, f5, f6, f7, g4, g5, g6, g7;
;     DSR128(f0, a0, 0); DSR128(g0, a0, 8192); DSR128(f1, a1, 0); DSR128(g1, a1, 8192); DSR128(f2, a2, 0); DSR128(g2, a2, 8192); DSR128(f3, a3, 0); DSR128(g3, a3, 8192);
;     asm volatile("s_waitcnt lgkmcnt(0)" : "+v"(f0), "+v"(g0), "+v"(f1), "+v"(g1), "+v"(f2), "+v"(g2), "+v"(f3), "+v"(g3) :: "memory");
;     DSR128(f4, a0, 128); DSR128(g4, a0, 8320); DSR128(f5, a1, 128); DSR128(g5, a1, 8320); DSR128(f6, a2, 128); DSR128(g6, a2, 8320); DSR128(f7, a3, 128); DSR128(g7, a3, 8320);
;     SBAR();
;     p0 = __builtin_amdgcn_mfma_f32_32x32x16_bf16(f0, qr[0], zi, 0, 0, 0); p1 = __builtin_amdgcn_mfma_f32_32x32x16_bf16(g0, qr[0], zi, 0, 0, 0);
;     p0 = __builtin_amdgcn_mfma_f32_32x32x16_bf16(f1, qr[1], p0, 0, 0, 0); p1 = __builtin_amdgcn_mfma_f32_32x32x16_bf16(g1, qr[1], p1, 0, 0, 0);
;     p0 = __builtin_amdgcn_mfma_f32_32x32x16_bf16(f2, qr[2], p0, 0, 0, 0); p1 = __builtin_amdgcn_mfma_f32_32x32x16_bf16(g2, qr[2], p1, 0, 0, 0);
;     p0 = __builtin_amdgcn_mfma_f32_32x32x16_bf16(f3, qr[3], p0, 0, 0, 0); p1 = __builtin_amdgcn_mfma_f32_32x32x16_bf16(g3, qr[3], p1, 0, 0, 0);
;     asm volatile("s_waitcnt lgkmcnt(0)" : "+v"(f4), "+v"(g4), "+v"(f5), "+v"(g5), "+v"(f6), "+v"(g6), "+v"(f7), "+v"(g7) :: "memory");
;     SBAR();
;     p0 = __builtin_amdgcn_mfma_f32_32x32x16_bf16(f4, qr[4], p0, 0, 0, 0); p1 = __builtin_amdgcn_mfma_f32_32x32x16_bf16(g4, qr[4], p1, 0, 0, 0);
;     p0 = __builtin_amdgcn_mfma_f32_32x32x16_bf16(f5, qr[5], p0, 0, 0, 0); p1 = __builtin_amdgcn_mfma_f32_32x32x16_bf16(g5, qr[5], p1, 0, 0, 0);
;     p0 = __builtin_amdgcn_mfma_f32_32x32x16_bf16(f6, qr[6], p0, 0, 0, 0); p1 = __builtin_amdgcn_mfma_f32_32x32x16_bf16(g6, qr[6], p1, 0, 0, 0);
;     p0 = __builtin_amdgcn_mfma_f32_32x32x16_bf16(f7, qr[7], p0, 0, 0, 0); p1 = __builtin_amdgcn_mfma_f32_32x32x16_bf16(g7, qr[7], p1, 0, 0, 0);
;     ...
; }
.Lmy_ldskip_2:
	s_add_i32 s12, s0, 0
	s_add_i32 s0, s12, 0xc000
	v_bfe_u32 v2, v151, s11, 1
	v_cmp_eq_u32_e32 vcc, 0, v2
	v_add_u32_e32 v2, s0, v170
	ds_read_b128 v[180:183], v2 offset:0
	ds_read_b128 v[184:187], v2 offset:0x2000
	v_add_u32_e32 v84, s0, v171
	ds_read_b128 v[188:191], v84 offset:0
	ds_read_b128 v[192:195], v84 offset:0x2000
	v_add_u32_e32 v85, s0, v172
	ds_read_b128 v[196:199], v85 offset:0
	ds_read_b128 v[200:203], v85 offset:0x2000
	v_add_u32_e32 v86, s0, v173
	ds_read_b128 v[204:207], v86 offset:0
	ds_read_b128 v[208:211], v86 offset:0x2000
	v_cndmask_b32_e32 v68, 0, v163, vcc
	s_waitcnt lgkmcnt(0)
	ds_read_b128 v[212:215], v2 offset:0x80
	ds_read_b128 v[216:219], v2 offset:0x2080
	ds_read_b128 v[220:223], v84 offset:0x80
	ds_read_b128 v[224:227], v84 offset:0x2080
	ds_read_b128 v[228:231], v85 offset:0x80
	ds_read_b128 v[232:235], v85 offset:0x2080
	ds_read_b128 v[236:239], v86 offset:0x80
	ds_read_b128 v[240:243], v86 offset:0x2080
	v_mov_b32_e32 v69, v68
	v_mov_b32_e32 v70, v68
	v_mov_b32_e32 v71, v68
	v_mov_b32_e32 v72, v68
	v_mov_b32_e32 v73, v68
	v_mov_b32_e32 v74, v68
	v_mov_b32_e32 v75, v68
	v_mov_b32_e32 v76, v68
	v_mov_b32_e32 v77, v68
	v_mov_b32_e32 v78, v68
	v_mov_b32_e32 v79, v68
	v_mov_b32_e32 v80, v68
	v_mov_b32_e32 v81, v68
	v_mov_b32_e32 v82, v68
	v_mov_b32_e32 v83, v68
	s_nop 1
	v_mfma_f32_32x32x16_bf16 v[84:99], v[180:183], v[100:103], v[68:83]
	v_mfma_f32_32x32x16_bf16 v[68:83], v[184:187], v[100:103], v[68:83]
	v_mfma_f32_32x32x16_bf16 v[84:99], v[188:191], v[104:107], v[84:99]
	v_mfma_f32_32x32x16_bf16 v[68:83], v[192:195], v[104:107], v[68:83]
	v_mfma_f32_32x32x16_bf16 v[84:99], v[196:199], v[108:111], v[84:99]
	v_mfma_f32_32x32x16_bf16 v[68:83], v[200:203], v[108:111], v[68:83]
	v_mfma_f32_32x32x16_bf16 v[84:99], v[204:207], v[112:115], v[84:99]
	v_mfma_f32_32x32x16_bf16 v[68:83], v[208:211], v[112:115], v[68:83]
	s_waitcnt lgkmcnt(0)
	v_mfma_f32_32x32x16_bf16 v[84:99], v[212:215], v[116:119], v[84:99]
	s_cmp_ge_i32 s9, s95
	v_mfma_f32_32x32x16_bf16 v[68:83], v[216:219], v[116:119], v[68:83]
	v_mfma_f32_32x32x16_bf16 v[84:99], v[220:223], v[120:123], v[84:99]
	v_mfma_f32_32x32x16_bf16 v[68:83], v[224:227], v[120:123], v[68:83]
	v_mfma_f32_32x32x16_bf16 v[84:99], v[228:231], v[124:127], v[84:99]
	v_mfma_f32_32x32x16_bf16 v[68:83], v[232:235], v[124:127], v[68:83]
	v_mfma_f32_32x32x16_bf16 v[84:99], v[236:239], v[128:131], v[84:99]
	v_mfma_f32_32x32x16_bf16 v[68:83], v[240:243], v[128:131], v[68:83]
	s_mul_i32 s99, s10, 0x4000
	v_add_u32_e32 v247, s99, v176
	ds_read_b64_tr_b16 v[214:215], v247 offset:0
	ds_read_b64_tr_b16 v[216:217], v247 offset:2048
	ds_read_b64_tr_b16 v[218:219], v247 offset:4096
	ds_read_b64_tr_b16 v[220:221], v247 offset:6144
	ds_read_b64_tr_b16 v[222:223], v247 offset:8192
	ds_read_b64_tr_b16 v[224:225], v247 offset:10240
	ds_read_b64_tr_b16 v[226:227], v247 offset:12288
	ds_read_b64_tr_b16 v[228:229], v247 offset:14336
	ds_read_b64_tr_b16 v[230:231], v247 offset:512
	ds_read_b64_tr_b16 v[232:233], v247 offset:2560
	ds_read_b64_tr_b16 v[234:235], v247 offset:4608
	ds_read_b64_tr_b16 v[236:237], v247 offset:6656
	ds_read_b64_tr_b16 v[238:239], v247 offset:8704
	ds_read_b64_tr_b16 v[240:241], v247 offset:10752
	ds_read_b64_tr_b16 v[242:243], v247 offset:12800
	ds_read_b64_tr_b16 v[244:245], v247 offset:14848
	s_cbranch_scc1 .LBB0_3504
	ds_read_b32 v180, v177 offset:0xec
	ds_read_b32 v182, v177 offset:0x6c
	ds_read_b32 v181, v177 offset:0xe8
	ds_read_b32 v183, v177 offset:0x68
	ds_read_b32 v184, v177 offset:0xe4
	ds_read_b32 v186, v177 offset:0x64
	ds_read_b32 v185, v177 offset:0xe0
	ds_read_b32 v187, v177 offset:0x60
	ds_read_b32 v188, v177 offset:0xcc
	ds_read_b32 v190, v177 offset:0x4c
	ds_read_b32 v189, v177 offset:0xc8
	ds_read_b32 v191, v177 offset:0x48
	ds_read_b32 v192, v177 offset:0xc4
	ds_read_b32 v194, v177 offset:0x44
	ds_read_b32 v193, v177 offset:0xc0
	ds_read_b32 v195, v177 offset:64
	ds_read_b32 v196, v177 offset:0xac
	ds_read_b32 v198, v177 offset:44
	ds_read_b32 v197, v177 offset:0xa8
	ds_read_b32 v199, v177 offset:40
	ds_read_b32 v200, v177 offset:0xa4
	ds_read_b32 v202, v177 offset:36
	ds_read_b32 v201, v177 offset:0xa0
	ds_read_b32 v203, v177 offset:32
	ds_read_b32 v204, v177 offset:0x8c
	ds_read_b32 v206, v177 offset:12
	ds_read_b32 v205, v177 offset:0x88
	ds_read_b32 v207, v177 offset:8
	ds_read_b32 v208, v177 offset:0x84
	ds_read_b32 v210, v177 offset:4
	ds_read_b32 v209, v177 offset:0x80
	ds_read_b32 v211, v177 offset:0
	s_nop 0
	s_waitcnt lgkmcnt(0)
	s_nop 8
	v_pk_add_f32 v[98:99], v[98:99], v[208:209]
	v_pk_add_f32 v[96:97], v[96:97], v[204:205]
	v_pk_add_f32 v[94:95], v[94:95], v[200:201]
	v_pk_add_f32 v[92:93], v[92:93], v[196:197]
	v_pk_add_f32 v[90:91], v[90:91], v[192:193]
	v_pk_add_f32 v[88:89], v[88:89], v[188:189]
	v_pk_add_f32 v[86:87], v[86:87], v[184:185]
	v_pk_add_f32 v[84:85], v[84:85], v[180:181]
	v_pk_add_f32 v[82:83], v[82:83], v[210:211]
	v_pk_add_f32 v[80:81], v[80:81], v[206:207]
	v_pk_add_f32 v[78:79], v[78:79], v[202:203]
	v_pk_add_f32 v[76:77], v[76:77], v[198:199]
	v_pk_add_f32 v[74:75], v[74:75], v[194:195]
	v_pk_add_f32 v[72:73], v[72:73], v[190:191]
	v_pk_add_f32 v[70:71], v[70:71], v[186:187]
	v_pk_add_f32 v[68:69], v[68:69], v[182:183]

; __device__ __forceinline__ void pv_tile(f32x16* o, int vb, bf16x8 pa0, bf16x8 pa1, bf16x8 pa2, bf16x8 pa3) {
;     ...
;     PV_D0(0); PV_D0(1); PV_D0(2); PV_D0(3);
;     ...
; }
; template <int MODE>
; __device__ __forceinline__ void attn_branch(Frame& F, const bf16_t* Kp, const bf16_t* Vp, int j_lo, int j_hi, int sb, const bf16x8* qr, unsigned smask, f32x16* o, float& l_out) {
;     ...
;         pv_tile(o, vb0 + vs * SHM_T, pa0, pa1, pa2, pa3);
;         if (t + 2 < NT) tile_write(T, lds, t & 1, vs == 0 ? 2 : vs - 1, sr, sc);
.LBB0_3513:
	s_lshl_b32 s13, s10, 14
	s_waitcnt lgkmcnt(0)
	s_nop 0
	v_mfma_f32_32x32x16_bf16 v[52:67], v[68:71], v[214:217], v[52:67]
	ds_read_b64_tr_b16 v[214:215], v247 offset:1024
	ds_read_b64_tr_b16 v[216:217], v247 offset:3072
	v_mfma_f32_32x32x16_bf16 v[52:67], v[72:75], v[218:221], v[52:67]
	ds_read_b64_tr_b16 v[218:219], v247 offset:5120
	ds_read_b64_tr_b16 v[220:221], v247 offset:7168
	v_mfma_f32_32x32x16_bf16 v[52:67], v[80:83], v[222:225], v[52:67]
	ds_read_b64_tr_b16 v[222:223], v247 offset:9216
	ds_read_b64_tr_b16 v[224:225], v247 offset:11264
	v_mfma_f32_32x32x16_bf16 v[52:67], v[76:79], v[226:229], v[52:67]
	ds_read_b64_tr_b16 v[226:227], v247 offset:13312
	ds_read_b64_tr_b16 v[228:229], v247 offset:15360
	v_mfma_f32_32x32x16_bf16 v[36:51], v[68:71], v[230:233], v[36:51]
	ds_read_b64_tr_b16 v[230:231], v247 offset:1536
	ds_read_b64_tr_b16 v[232:233], v247 offset:3584
	v_mfma_f32_32x32x16_bf16 v[36:51], v[72:75], v[234:237], v[36:51]
	ds_read_b64_tr_b16 v[234:235], v247 offset:5632
	ds_read_b64_tr_b16 v[236:237], v247 offset:7680
	v_mfma_f32_32x32x16_bf16 v[36:51], v[80:83], v[238:241], v[36:51]
	ds_read_b64_tr_b16 v[238:239], v247 offset:9728
	ds_read_b64_tr_b16 v[240:241], v247 offset:11776
	v_mfma_f32_32x32x16_bf16 v[36:51], v[76:79], v[242:245], v[36:51]
	ds_read_b64_tr_b16 v[242:243], v247 offset:13824
	ds_read_b64_tr_b16 v[244:245], v247 offset:15872
	s_waitcnt lgkmcnt(8)
	s_nop 0
	v_mfma_f32_32x32x16_bf16 v[20:35], v[68:71], v[214:217], v[20:35]
	v_mfma_f32_32x32x16_bf16 v[20:35], v[72:75], v[218:221], v[20:35]
	v_mfma_f32_32x32x16_bf16 v[20:35], v[80:83], v[222:225], v[20:35]
	v_mfma_f32_32x32x16_bf16 v[20:35], v[76:79], v[226:229], v[20:35]
	s_waitcnt lgkmcnt(0)
	s_nop 0
	v_mfma_f32_32x32x16_bf16 v[4:19], v[68:71], v[230:233], v[4:19]
	v_mfma_f32_32x32x16_bf16 v[4:19], v[72:75], v[234:237], v[4:19]
	v_mfma_f32_32x32x16_bf16 v[4:19], v[80:83], v[238:241], v[4:19]
	v_mfma_f32_32x32x16_bf16 v[4:19], v[76:79], v[242:245], v[4:19]
	s_andn2_b64 vcc, exec, s[0:1]
	s_cbranch_vccnz .LBB0_3515
	s_addk_i32 s13, 0xc000
	s_cmp_lg_u32 s10, 0
	s_cselect_b32 s0, s13, 0x8000
	v_add_u32_e32 v68, s0, v168
	v_add3_u32 v70, s12, v159, v165
	v_add3_u32 v69, v68, v169, v167
	v_add3_u32 v68, v68, v166, v167
	s_waitcnt vmcnt(3)
	ds_write_b128 v70, v[132:135] offset:49152
	s_waitcnt vmcnt(2)
	ds_write_b128 v70, v[136:139] offset:57344
	s_waitcnt vmcnt(1)
	ds_write_b128 v68, v[140:143]
	s_waitcnt vmcnt(0)
	ds_write_b128 v69, v[144:147]

; __device__ __forceinline__ void qkt(f32x16& p0, f32x16& p1, const LAS unsigned char* Kt, int r32, int hi, const bf16x8* qr, float init) {
;     f32x16 zi;
; #pragma unroll
;     for (int r = 0; r < 16; ++r) zi[r] = init;
;     const int kt = (int)(uintptr_t)Kt;
;     const int a0 = kt + KSWZ(r32, (0 * 16 + hi * 8) * 2), a1 = kt + KSWZ(r32, (1 * 16 + hi * 8) * 2), a2 = kt + KSWZ(r32, (2 * 16 + hi * 8) * 2), a3 = kt + KSWZ(r32, (3 * 16 + hi * 8) * 2);
;     ...
;     bf16x8 f0, f1, f2, f3, g0, g1, g2, g3, f4, f5, f6, f7, g4, g5, g6, g7;
;     DSR128(f0, a0, 0); DSR128(g0, a0, 8192); DSR128(f1, a1, 0); DSR128(g1, a1, 8192); DSR128(f2, a2, 0); DSR128(g2, a2, 8192); DSR128(f3, a3, 0); DSR128(g3, a3, 8192);
;     asm volatile("s_waitcnt lgkmcnt(0)" : "+v"(f0), "+v"(g0), "+v"(f1), "+v"(g1), "+v"(f2), "+v"(g2), "+v"(f3), "+v"(g3) :: "memory");
;     DSR128(f4, a0, 128); DSR128(g4, a0, 8320); DSR128(f5, a1, 128); DSR128(g5, a1, 8320); DSR128(f6, a2, 128); DSR128(g6, a2, 8320); DSR128(f7, a3, 128); DSR128(g7, a3, 8320);
;     SBAR();
;     p0 = __builtin_amdgcn_mfma_f32_32x32x16_bf16(f0, qr[0], zi, 0, 0, 0); p1 = __builtin_amdgcn_mfma_f32_32x32x16_bf16(g0, qr[0], zi, 0, 0, 0);
;     p0 = __builtin_amdgcn_mfma_f32_32x32x16_bf16(f1, qr[1], p0, 0, 0, 0); p1 = __builtin_amdgcn_mfma_f32_32x32x16_bf16(g1, qr[1], p1, 0, 0, 0);
;     p0 = __builtin_amdgcn_mfma_f32_32x32x16_bf16(f2, qr[2], p0, 0, 0, 0); p1 = __builtin_amdgcn_mfma_f32_32x32x16_bf16(g2, qr[2], p1, 0, 0, 0);
;     p0 = __builtin_amdgcn_mfma_f32_32x32x16_bf16(f3, qr[3], p0, 0, 0, 0); p1 = __builtin_amdgcn_mfma_f32_32x32x16_bf16(g3, qr[3], p1, 0, 0, 0);
;     asm volatile("s_waitcnt lgkmcnt(0)" : "+v"(f4), "+v"(g4), "+v"(f5), "+v"(g5), "+v"(f6), "+v"(g6), "+v"(f7), "+v"(g7) :: "memory");
;     SBAR();
;     p0 = __builtin_amdgcn_mfma_f32_32x32x16_bf16(f4, qr[4], p0, 0, 0, 0); p1 = __builtin_amdgcn_mfma_f32_32x32x16_bf16(g4, qr[4], p1, 0, 0, 0);
;     p0 = __builtin_amdgcn_mfma_f32_32x32x16_bf16(f5, qr[5], p0, 0, 0, 0); p1 = __builtin_amdgcn_mfma_f32_32x32x16_bf16(g5, qr[5], p1, 0, 0, 0);
;     p0 = __builtin_amdgcn_mfma_f32_32x32x16_bf16(f6, qr[6], p0, 0, 0, 0); p1 = __builtin_amdgcn_mfma_f32_32x32x16_bf16(g6, qr[6], p1, 0, 0, 0);
;     p0 = __builtin_amdgcn_mfma_f32_32x32x16_bf16(f7, qr[7], p0, 0, 0, 0); p1 = __builtin_amdgcn_mfma_f32_32x32x16_bf16(g7, qr[7], p1, 0, 0, 0);
;     ...
; }
.Lmy_ldskip_3:
	s_add_i32 s12, s0, 0
	s_add_i32 s0, s12, 0xc000
	v_add_u32_e32 v2, s0, v169
	ds_read_b128 v[68:71], v2 offset:0
	ds_read_b128 v[72:75], v2 offset:0x2000
	v_add_u32_e32 v76, s0, v170
	ds_read_b128 v[180:183], v76 offset:0
	ds_read_b128 v[184:187], v76 offset:0x2000
	v_add_u32_e32 v77, s0, v171
	ds_read_b128 v[188:191], v77 offset:0
	ds_read_b128 v[192:195], v77 offset:0x2000
	v_add_u32_e32 v78, s0, v172
	ds_read_b128 v[196:199], v78 offset:0
	ds_read_b128 v[200:203], v78 offset:0x2000
	s_nop 0
	s_waitcnt lgkmcnt(0)
	ds_read_b128 v[204:207], v2 offset:0x80
	ds_read_b128 v[208:211], v2 offset:0x2080
	ds_read_b128 v[212:215], v76 offset:0x80
	ds_read_b128 v[216:219], v76 offset:0x2080
	ds_read_b128 v[220:223], v77 offset:0x80
	ds_read_b128 v[224:227], v77 offset:0x2080
	ds_read_b128 v[228:231], v78 offset:0x80
	ds_read_b128 v[232:235], v78 offset:0x2080
	s_nop 0
	v_mfma_f32_32x32x16_bf16 v[84:99], v[68:71], v[100:103], 0
	v_mfma_f32_32x32x16_bf16 v[68:83], v[72:75], v[100:103], 0
	v_mfma_f32_32x32x16_bf16 v[84:99], v[180:183], v[104:107], v[84:99]
	v_mfma_f32_32x32x16_bf16 v[68:83], v[184:187], v[104:107], v[68:83]
	v_mfma_f32_32x32x16_bf16 v[84:99], v[188:191], v[108:111], v[84:99]
	v_mfma_f32_32x32x16_bf16 v[68:83], v[192:195], v[108:111], v[68:83]
	v_mfma_f32_32x32x16_bf16 v[84:99], v[196:199], v[112:115], v[84:99]
	v_mfma_f32_32x32x16_bf16 v[68:83], v[200:203], v[112:115], v[68:83]
	s_waitcnt lgkmcnt(0)
	v_mfma_f32_32x32x16_bf16 v[84:99], v[204:207], v[116:119], v[84:99]
	s_add_i32 s0, s54, s9
	s_cmp_ge_i32 s0, s95
	v_mfma_f32_32x32x16_bf16 v[68:83], v[208:211], v[116:119], v[68:83]
	v_mfma_f32_32x32x16_bf16 v[84:99], v[212:215], v[120:123], v[84:99]
	v_mfma_f32_32x32x16_bf16 v[68:83], v[216:219], v[120:123], v[68:83]
	v_mfma_f32_32x32x16_bf16 v[84:99], v[220:223], v[124:127], v[84:99]
	v_mfma_f32_32x32x16_bf16 v[68:83], v[224:227], v[124:127], v[68:83]
	v_mfma_f32_32x32x16_bf16 v[84:99], v[228:231], v[128:131], v[84:99]
	v_mfma_f32_32x32x16_bf16 v[68:83], v[232:235], v[128:131], v[68:83]
	s_mul_i32 s99, s11, 0x4000
	v_add_u32_e32 v247, s99, v175
	ds_read_b64_tr_b16 v[214:215], v247 offset:0
	ds_read_b64_tr_b16 v[216:217], v247 offset:2048
	ds_read_b64_tr_b16 v[218:219], v247 offset:4096
	ds_read_b64_tr_b16 v[220:221], v247 offset:6144
	ds_read_b64_tr_b16 v[222:223], v247 offset:8192
	ds_read_b64_tr_b16 v[224:225], v247 offset:10240
	ds_read_b64_tr_b16 v[226:227], v247 offset:12288
	ds_read_b64_tr_b16 v[228:229], v247 offset:14336
	ds_read_b64_tr_b16 v[230:231], v247 offset:512
	ds_read_b64_tr_b16 v[232:233], v247 offset:2560
	ds_read_b64_tr_b16 v[234:235], v247 offset:4608
	ds_read_b64_tr_b16 v[236:237], v247 offset:6656
	ds_read_b64_tr_b16 v[238:239], v247 offset:8704
	ds_read_b64_tr_b16 v[240:241], v247 offset:10752
	ds_read_b64_tr_b16 v[242:243], v247 offset:12800
	ds_read_b64_tr_b16 v[244:245], v247 offset:14848
	s_cbranch_scc1 .LBB0_3527
	ds_read_b32 v180, v176 offset:0xec
	ds_read_b32 v182, v176 offset:0x6c
	ds_read_b32 v181, v176 offset:0xe8
	ds_read_b32 v183, v176 offset:0x68
	ds_read_b32 v184, v176 offset:0xe4
	ds_read_b32 v186, v176 offset:0x64
	ds_read_b32 v185, v176 offset:0xe0
	ds_read_b32 v187, v176 offset:0x60
	ds_read_b32 v188, v176 offset:0xcc
	ds_read_b32 v190, v176 offset:0x4c
	ds_read_b32 v189, v176 offset:0xc8
	ds_read_b32 v191, v176 offset:0x48
	ds_read_b32 v192, v176 offset:0xc4
	ds_read_b32 v194, v176 offset:0x44
	ds_read_b32 v193, v176 offset:0xc0
	ds_read_b32 v195, v176 offset:64
	ds_read_b32 v196, v176 offset:0xac
	ds_read_b32 v198, v176 offset:44
	ds_read_b32 v197, v176 offset:0xa8
	ds_read_b32 v199, v176 offset:40
	ds_read_b32 v200, v176 offset:0xa4
	ds_read_b32 v202, v176 offset:36
	ds_read_b32 v201, v176 offset:0xa0
	ds_read_b32 v203, v176 offset:32
	ds_read_b32 v204, v176 offset:0x8c
	ds_read_b32 v206, v176 offset:12
	ds_read_b32 v205, v176 offset:0x88
	ds_read_b32 v207, v176 offset:8
	ds_read_b32 v208, v176 offset:0x84
	ds_read_b32 v210, v176 offset:4
	ds_read_b32 v209, v176 offset:0x80
	ds_read_b32 v211, v176 offset:0
	s_nop 0
	s_waitcnt lgkmcnt(0)
	s_nop 8
	v_pk_add_f32 v[98:99], v[98:99], v[208:209]
	v_pk_add_f32 v[96:97], v[96:97], v[204:205]
	v_pk_add_f32 v[94:95], v[94:95], v[200:201]
	v_pk_add_f32 v[92:93], v[92:93], v[196:197]
	v_pk_add_f32 v[90:91], v[90:91], v[192:193]
	v_pk_add_f32 v[88:89], v[88:89], v[188:189]
	v_pk_add_f32 v[86:87], v[86:87], v[184:185]
	v_pk_add_f32 v[84:85], v[84:85], v[180:181]
	v_pk_add_f32 v[82:83], v[82:83], v[210:211]
	v_pk_add_f32 v[80:81], v[80:81], v[206:207]
	v_pk_add_f32 v[78:79], v[78:79], v[202:203]
	v_pk_add_f32 v[76:77], v[76:77], v[198:199]
	v_pk_add_f32 v[74:75], v[74:75], v[194:195]
	v_pk_add_f32 v[72:73], v[72:73], v[190:191]
	v_pk_add_f32 v[70:71], v[70:71], v[186:187]
	v_pk_add_f32 v[68:69], v[68:69], v[182:183]

; __device__ __forceinline__ void pv_tile(f32x16* o, int vb, bf16x8 pa0, bf16x8 pa1, bf16x8 pa2, bf16x8 pa3) {
;     ...
;     PV_D0(0); PV_D0(1); PV_D0(2); PV_D0(3);
;     ...
; }
; template <int MODE>
; __device__ __forceinline__ void attn_branch(Frame& F, const bf16_t* Kp, const bf16_t* Vp, int j_lo, int j_hi, int sb, const bf16x8* qr, unsigned smask, f32x16* o, float& l_out) {
;     ...
;         pv_tile(o, vb0 + vs * SHM_T, pa0, pa1, pa2, pa3);
;         if (t + 2 < NT) tile_write(T, lds, t & 1, vs == 0 ? 2 : vs - 1, sr, sc);
.LBB0_3536:
	s_lshl_b32 s13, s11, 14
	s_waitcnt lgkmcnt(0)
	s_nop 0
	v_mfma_f32_32x32x16_bf16 v[52:67], v[68:71], v[214:217], v[52:67]
	ds_read_b64_tr_b16 v[214:215], v247 offset:1024
	ds_read_b64_tr_b16 v[216:217], v247 offset:3072
	v_mfma_f32_32x32x16_bf16 v[52:67], v[72:75], v[218:221], v[52:67]
	ds_read_b64_tr_b16 v[218:219], v247 offset:5120
	ds_read_b64_tr_b16 v[220:221], v247 offset:7168
	v_mfma_f32_32x32x16_bf16 v[52:67], v[80:83], v[222:225], v[52:67]
	ds_read_b64_tr_b16 v[222:223], v247 offset:9216
	ds_read_b64_tr_b16 v[224:225], v247 offset:11264
	v_mfma_f32_32x32x16_bf16 v[52:67], v[76:79], v[226:229], v[52:67]
	ds_read_b64_tr_b16 v[226:227], v247 offset:13312
	ds_read_b64_tr_b16 v[228:229], v247 offset:15360
	v_mfma_f32_32x32x16_bf16 v[36:51], v[68:71], v[230:233], v[36:51]
	ds_read_b64_tr_b16 v[230:231], v247 offset:1536
	ds_read_b64_tr_b16 v[232:233], v247 offset:3584
	v_mfma_f32_32x32x16_bf16 v[36:51], v[72:75], v[234:237], v[36:51]
	ds_read_b64_tr_b16 v[234:235], v247 offset:5632
	ds_read_b64_tr_b16 v[236:237], v247 offset:7680
	v_mfma_f32_32x32x16_bf16 v[36:51], v[80:83], v[238:241], v[36:51]
	ds_read_b64_tr_b16 v[238:239], v247 offset:9728
	ds_read_b64_tr_b16 v[240:241], v247 offset:11776
	v_mfma_f32_32x32x16_bf16 v[36:51], v[76:79], v[242:245], v[36:51]
	ds_read_b64_tr_b16 v[242:243], v247 offset:13824
	ds_read_b64_tr_b16 v[244:245], v247 offset:15872
	s_waitcnt lgkmcnt(8)
	s_nop 0
	v_mfma_f32_32x32x16_bf16 v[20:35], v[68:71], v[214:217], v[20:35]
	v_mfma_f32_32x32x16_bf16 v[20:35], v[72:75], v[218:221], v[20:35]
	v_mfma_f32_32x32x16_bf16 v[20:35], v[80:83], v[222:225], v[20:35]
	v_mfma_f32_32x32x16_bf16 v[20:35], v[76:79], v[226:229], v[20:35]
	s_waitcnt lgkmcnt(0)
	s_nop 0
	v_mfma_f32_32x32x16_bf16 v[4:19], v[68:71], v[230:233], v[4:19]
	v_mfma_f32_32x32x16_bf16 v[4:19], v[72:75], v[234:237], v[4:19]
	v_mfma_f32_32x32x16_bf16 v[4:19], v[80:83], v[238:241], v[4:19]
	v_mfma_f32_32x32x16_bf16 v[4:19], v[76:79], v[242:245], v[4:19]
	s_andn2_b64 vcc, exec, s[0:1]
	s_cbranch_vccnz .LBB0_3538
	s_addk_i32 s13, 0xc000
	s_cmp_lg_u32 s11, 0
	s_cselect_b32 s0, s13, 0x8000
	v_add_u32_e32 v68, s0, v167
	v_add3_u32 v70, s12, v159, v161
	v_add3_u32 v69, v68, v168, v166
	v_add3_u32 v68, v68, v165, v166
	s_waitcnt vmcnt(3)
	ds_write_b128 v70, v[132:135] offset:49152
	s_waitcnt vmcnt(2)
	ds_write_b128 v70, v[136:139] offset:57344
	s_waitcnt vmcnt(1)
	ds_write_b128 v68, v[140:143]
	s_waitcnt vmcnt(0)
	ds_write_b128 v69, v[144:147]

; __global__ void __launch_bounds__(512, 2) mk_fwd(Args args) {
	.amdhsa_kernel _Z6mk_fwd4Args
		.amdhsa_group_segment_fixed_size 0
		.amdhsa_private_segment_fixed_size 0
		.amdhsa_kernarg_size 464
		.amdhsa_user_sgpr_count 2
		.amdhsa_user_sgpr_dispatch_ptr 0
		.amdhsa_user_sgpr_queue_ptr 0
		.amdhsa_user_sgpr_kernarg_segment_ptr 1
		.amdhsa_user_sgpr_dispatch_id 0
		.amdhsa_user_sgpr_kernarg_preload_length 0
		.amdhsa_user_sgpr_kernarg_preload_offset 0
		.amdhsa_user_sgpr_private_segment_size 0
		.amdhsa_uses_dynamic_stack 0
		.amdhsa_enable_private_segment 0
		.amdhsa_system_sgpr_workgroup_id_x 1
		.amdhsa_system_sgpr_workgroup_id_y 0
		.amdhsa_system_sgpr_workgroup_id_z 0
		.amdhsa_system_sgpr_workgroup_info 0
		.amdhsa_system_vgpr_workitem_id 0
		.amdhsa_next_free_vgpr 248
		.amdhsa_next_free_sgpr 100
		.amdhsa_accum_offset 248
		.amdhsa_reserve_vcc 1
		.amdhsa_float_round_mode_32 0
		.amdhsa_float_round_mode_16_64 0
		.amdhsa_float_denorm_mode_32 3
		.amdhsa_float_denorm_mode_16_64 3
		.amdhsa_dx10_clamp 1
		.amdhsa_ieee_mode 1
		.amdhsa_fp16_overflow 0
		.amdhsa_tg_split 0
		.amdhsa_exception_fp_ieee_invalid_op 0
		.amdhsa_exception_fp_denorm_src 0
		.amdhsa_exception_fp_ieee_div_zero 0
		.amdhsa_exception_fp_ieee_overflow 0
		.amdhsa_exception_fp_ieee_underflow 0
		.amdhsa_exception_fp_ieee_inexact 0
		.amdhsa_exception_int_div_zero 0
	.end_amdhsa_kernel

; __global__ void __launch_bounds__(512, 2) mk_fwd(Args args) {
amdhsa.kernels:
  - .agpr_count:     0
    .args:
      - .offset:         0
        .size:           208
        .value_kind:     by_value
      - .offset:         208
        .size:           4
        .value_kind:     hidden_block_count_x
      - .offset:         212
        .size:           4
        .value_kind:     hidden_block_count_y
      - .offset:         216
        .size:           4
        .value_kind:     hidden_block_count_z
      - .offset:         220
        .size:           2
        .value_kind:     hidden_group_size_x
      - .offset:         222
        .size:           2
        .value_kind:     hidden_group_size_y
      - .offset:         224
        .size:           2
        .value_kind:     hidden_group_size_z
      - .offset:         226
        .size:           2
        .value_kind:     hidden_remainder_x
      - .offset:         228
        .size:           2
        .value_kind:     hidden_remainder_y
      - .offset:         230
        .size:           2
        .value_kind:     hidden_remainder_z
      - .offset:         248
        .size:           8
        .value_kind:     hidden_global_offset_x
      - .offset:         256
        .size:           8
        .value_kind:     hidden_global_offset_y
      - .offset:         264
        .size:           8
        .value_kind:     hidden_global_offset_z
      - .offset:         272
        .size:           2
        .value_kind:     hidden_grid_dims
      - .offset:         328
        .size:           4
        .value_kind:     hidden_dynamic_lds_size
    .group_segment_fixed_size: 0
    .kernarg_segment_align: 8
    .kernarg_segment_size: 464
    .language:       OpenCL C
    .language_version:
      - 2
      - 0
    .max_flat_workgroup_size: 512
    .name:           _Z6mk_fwd4Args
    .private_segment_fixed_size: 0
    .sgpr_count:     106
    .sgpr_spill_count: 53
    .symbol:         _Z6mk_fwd4Args.kd
    .uniform_work_group_size: 1
    .uses_dynamic_stack: false
    .vgpr_count:     248
    .vgpr_spill_count: 0
    .wavefront_size: 64
